# phase 0 modulation GEMV: all 64 w_mod loads of a lane issued up front (touch) so the k-loop hits L2
# speedup vs baseline: 1.0106x; 1.0046x over previous
; DI void phase0(const Params& p, unsigned char* smem) {
;     ...
;             const int col = item * 32 + (lane & 31), kh = lane >> 5;
;             float acc[17];
; #pragma unroll
;             for (int b = 0; b < 17; ++b) acc[b] = 0.f;
; #pragma unroll 4
;             for (int kk = 0; kk < 64; ++kk) {
;                 const int k = 128 * wave + 2 * kk + kh; const float wv = p.w_mod[(size_t)k * NMODC + col];
; #pragma unroll
;                 for (int b = 0; b < 17; ++b) acc[b] += sc[b * 1024 + k] * wv;
;             }
.LBB0_13:
	v_ashrrev_i32_e32 v7, 31, v6
	v_lshlrev_b64 v[14:15], 2, v[6:7]
	v_lshl_add_u64 v[28:29], v[4:5], 0, v[14:15]
	v_lshl_add_u64 v[30:31], v[8:9], 0, v[14:15]
	v_lshl_add_u64 v[32:33], v[10:11], 0, v[14:15]
	v_lshl_add_u64 v[34:35], v[12:13], 0, v[14:15]
	s_mov_b32 s6, 0
	v_mov_b32_e32 v36, 0
	v_mov_b32_e32 v37, v3
	v_mov_b32_e32 v26, 0
	v_mov_b32_e32 v27, v3
	v_mov_b32_e32 v24, 0
	v_mov_b32_e32 v25, v3
	v_mov_b32_e32 v22, 0
	v_mov_b32_e32 v23, v3
	v_mov_b32_e32 v20, 0
	v_mov_b32_e32 v21, v3
	v_mov_b32_e32 v18, 0
	v_mov_b32_e32 v19, v3
	v_mov_b32_e32 v16, 0
	v_mov_b32_e32 v17, v3
	v_mov_b32_e32 v14, 0
	v_mov_b32_e32 v15, v3
	v_mov_b32_e32 v7, 0
	v_mov_b32_e32 v200, v28
	v_mov_b32_e32 v201, v29
	v_mov_b32_e32 v202, v30
	v_mov_b32_e32 v203, v31
	v_mov_b32_e32 v204, v32
	v_mov_b32_e32 v205, v33
	v_mov_b32_e32 v206, v34
	v_mov_b32_e32 v207, v35
	global_load_dword v208, v[206:207], off
	global_load_dword v209, v[204:205], off
	global_load_dword v210, v[202:203], off
	global_load_dword v211, v[200:201], off
	v_lshl_add_u64 v[200:201], v[200:201], 0, s[14:15]
	v_lshl_add_u64 v[202:203], v[202:203], 0, s[14:15]
	v_lshl_add_u64 v[204:205], v[204:205], 0, s[14:15]
	v_lshl_add_u64 v[206:207], v[206:207], 0, s[14:15]
	global_load_dword v208, v[206:207], off
	global_load_dword v209, v[204:205], off
	global_load_dword v210, v[202:203], off
	global_load_dword v211, v[200:201], off
	v_lshl_add_u64 v[200:201], v[200:201], 0, s[14:15]
	v_lshl_add_u64 v[202:203], v[202:203], 0, s[14:15]
	v_lshl_add_u64 v[204:205], v[204:205], 0, s[14:15]
	v_lshl_add_u64 v[206:207], v[206:207], 0, s[14:15]
	global_load_dword v208, v[206:207], off
	global_load_dword v209, v[204:205], off
	global_load_dword v210, v[202:203], off
	global_load_dword v211, v[200:201], off
	v_lshl_add_u64 v[200:201], v[200:201], 0, s[14:15]
	v_lshl_add_u64 v[202:203], v[202:203], 0, s[14:15]
	v_lshl_add_u64 v[204:205], v[204:205], 0, s[14:15]
	v_lshl_add_u64 v[206:207], v[206:207], 0, s[14:15]
	global_load_dword v208, v[206:207], off
	global_load_dword v209, v[204:205], off
	global_load_dword v210, v[202:203], off
	global_load_dword v211, v[200:201], off
	v_lshl_add_u64 v[200:201], v[200:201], 0, s[14:15]
	v_lshl_add_u64 v[202:203], v[202:203], 0, s[14:15]
	v_lshl_add_u64 v[204:205], v[204:205], 0, s[14:15]
	v_lshl_add_u64 v[206:207], v[206:207], 0, s[14:15]
	global_load_dword v208, v[206:207], off
	global_load_dword v209, v[204:205], off
	global_load_dword v210, v[202:203], off
	global_load_dword v211, v[200:201], off
	v_lshl_add_u64 v[200:201], v[200:201], 0, s[14:15]
	v_lshl_add_u64 v[202:203], v[202:203], 0, s[14:15]
	v_lshl_add_u64 v[204:205], v[204:205], 0, s[14:15]
	v_lshl_add_u64 v[206:207], v[206:207], 0, s[14:15]
	global_load_dword v208, v[206:207], off
	global_load_dword v209, v[204:205], off
	global_load_dword v210, v[202:203], off
	global_load_dword v211, v[200:201], off
	v_lshl_add_u64 v[200:201], v[200:201], 0, s[14:15]
	v_lshl_add_u64 v[202:203], v[202:203], 0, s[14:15]
	v_lshl_add_u64 v[204:205], v[204:205], 0, s[14:15]
	v_lshl_add_u64 v[206:207], v[206:207], 0, s[14:15]
	global_load_dword v208, v[206:207], off
	global_load_dword v209, v[204:205], off
	global_load_dword v210, v[202:203], off
	global_load_dword v211, v[200:201], off
	v_lshl_add_u64 v[200:201], v[200:201], 0, s[14:15]
	v_lshl_add_u64 v[202:203], v[202:203], 0, s[14:15]
	v_lshl_add_u64 v[204:205], v[204:205], 0, s[14:15]
	v_lshl_add_u64 v[206:207], v[206:207], 0, s[14:15]
	global_load_dword v208, v[206:207], off
	global_load_dword v209, v[204:205], off
	global_load_dword v210, v[202:203], off
	global_load_dword v211, v[200:201], off
	v_lshl_add_u64 v[200:201], v[200:201], 0, s[14:15]
	v_lshl_add_u64 v[202:203], v[202:203], 0, s[14:15]
	v_lshl_add_u64 v[204:205], v[204:205], 0, s[14:15]
	v_lshl_add_u64 v[206:207], v[206:207], 0, s[14:15]
	global_load_dword v208, v[206:207], off
	global_load_dword v209, v[204:205], off
	global_load_dword v210, v[202:203], off
	global_load_dword v211, v[200:201], off
	v_lshl_add_u64 v[200:201], v[200:201], 0, s[14:15]
	v_lshl_add_u64 v[202:203], v[202:203], 0, s[14:15]
	v_lshl_add_u64 v[204:205], v[204:205], 0, s[14:15]
	v_lshl_add_u64 v[206:207], v[206:207], 0, s[14:15]
	global_load_dword v208, v[206:207], off
	global_load_dword v209, v[204:205], off
	global_load_dword v210, v[202:203], off
	global_load_dword v211, v[200:201], off
	v_lshl_add_u64 v[200:201], v[200:201], 0, s[14:15]
	v_lshl_add_u64 v[202:203], v[202:203], 0, s[14:15]
	v_lshl_add_u64 v[204:205], v[204:205], 0, s[14:15]
	v_lshl_add_u64 v[206:207], v[206:207], 0, s[14:15]
	global_load_dword v208, v[206:207], off
	global_load_dword v209, v[204:205], off
	global_load_dword v210, v[202:203], off
	global_load_dword v211, v[200:201], off
	v_lshl_add_u64 v[200:201], v[200:201], 0, s[14:15]
	v_lshl_add_u64 v[202:203], v[202:203], 0, s[14:15]
	v_lshl_add_u64 v[204:205], v[204:205], 0, s[14:15]
	v_lshl_add_u64 v[206:207], v[206:207], 0, s[14:15]
	global_load_dword v208, v[206:207], off
	global_load_dword v209, v[204:205], off
	global_load_dword v210, v[202:203], off
	global_load_dword v211, v[200:201], off
	v_lshl_add_u64 v[200:201], v[200:201], 0, s[14:15]
	v_lshl_add_u64 v[202:203], v[202:203], 0, s[14:15]
	v_lshl_add_u64 v[204:205], v[204:205], 0, s[14:15]
	v_lshl_add_u64 v[206:207], v[206:207], 0, s[14:15]
	global_load_dword v208, v[206:207], off
	global_load_dword v209, v[204:205], off
	global_load_dword v210, v[202:203], off
	global_load_dword v211, v[200:201], off
	v_lshl_add_u64 v[200:201], v[200:201], 0, s[14:15]
	v_lshl_add_u64 v[202:203], v[202:203], 0, s[14:15]
	v_lshl_add_u64 v[204:205], v[204:205], 0, s[14:15]
	v_lshl_add_u64 v[206:207], v[206:207], 0, s[14:15]
	global_load_dword v208, v[206:207], off
	global_load_dword v209, v[204:205], off
	global_load_dword v210, v[202:203], off
	global_load_dword v211, v[200:201], off
	v_lshl_add_u64 v[200:201], v[200:201], 0, s[14:15]
	v_lshl_add_u64 v[202:203], v[202:203], 0, s[14:15]
	v_lshl_add_u64 v[204:205], v[204:205], 0, s[14:15]
	v_lshl_add_u64 v[206:207], v[206:207], 0, s[14:15]
	global_load_dword v208, v[206:207], off
	global_load_dword v209, v[204:205], off
	global_load_dword v210, v[202:203], off
	global_load_dword v211, v[200:201], off
	v_lshl_add_u64 v[200:201], v[200:201], 0, s[14:15]
	v_lshl_add_u64 v[202:203], v[202:203], 0, s[14:15]
	v_lshl_add_u64 v[204:205], v[204:205], 0, s[14:15]
	v_lshl_add_u64 v[206:207], v[206:207], 0, s[14:15]
	global_load_dword v208, v[206:207], off
	global_load_dword v209, v[204:205], off
	global_load_dword v210, v[202:203], off
	global_load_dword v211, v[200:201], off
